# merge phase: static s_setprio 1 on the leading virtual block as well (reset at the shared phase exit)
# baseline (speedup 1.0000x reference)
; __device__ __forceinline__ KargPtr karg() { KargPtr pp = (KargPtr)__builtin_amdgcn_kernarg_segment_ptr(); asm volatile("" : "+s"(pp)); return pp; }
; DI int vhalf() { return __builtin_amdgcn_readfirstlane((int)(threadIdx.x >> 8)); }
; DI int tidx() { int t = threadIdx.x & 255; asm volatile("" : "+v"(t)); return t; }
; DI int bidx() { int t = __builtin_amdgcn_readfirstlane((int)(blockIdx.x * 2 + (threadIdx.x >> 8))); asm volatile("" : "+s"(t)); return t; }
; DI void phase_merge(KargPtr p, int l, unsigned char* smem) {
;     const int tid = tidx(), lane = tid & 63, w = tid >> 6, wm = w >> 1, wn = w & 1, r = lane & 31, hh = lane >> 5;
;     const bf16_t* WL = p->wt + (size_t)l * W_LAYER;
;     for (int it = 0;; ++it) {
;         int mt, nt; if (!next_tile(it, 256, 8, mt, nt)) break;
; DI void run_phase(int ph, int l, unsigned char* smem_phys) {
;     ...
;     KargPtr p = karg();
;     unsigned char* smem = smem_phys + vhalf() * VSMEM;
;     switch (ph) {
;     case 0: phase_prep(p, smem); break;
;     case 1: if (bidx() == 0 && tidx() < 64) __hip_atomic_store((unsigned*)p->kmax + tidx(), 0u, __ATOMIC_RELAXED, __HIP_MEMORY_SCOPE_AGENT);
;             phase_norm((l == 0) ? p->x : p->out, p->g_mix + l * 1024, p->mod + (size_t)l * 8 * 6144, 0, 1, p->u); break;
;     case 2: phase_inproj(p, l, smem_phys); break;
;     case 3: phase_mla_up(p, l, smem); break;
;     case 4: phase_attn(p, smem); break;
;     case 5: phase_merge(p, l, smem); break;
.LBB0_545:
	s_andn2_b64 vcc, exec, s[4:5]
	s_cbranch_vccnz .LBB0_875
	s_lshr_b32 s2, s3, 8
	s_mul_i32 s2, s2, 0x12400
	s_add_i32 s3, s2, 0
	v_writelane_b32 v255, s2, 20
	s_cmp_lt_i32 s61, 3
	s_mov_b64 s[4:5], -1
	s_cbranch_scc1 .LBB0_663
	s_cmp_lt_i32 s61, 4
	s_cbranch_scc1 .LBB0_632
	s_cmp_gt_i32 s61, 4
	s_cbranch_scc0 .LBB0_562
	s_cmp_lg_u32 s3, 0
	s_cbranch_scc1 .Lmrg_noprio
	s_setprio 1
.Lmrg_noprio:
	v_mov_b32_e32 v2, v199
	s_load_dwordx2 s[4:5], s[0:1], 0xb0
	v_readlane_b32 s6, v255, 6
	v_readlane_b32 s7, v255, 7
	s_lshl_b64 s[6:7], s[6:7], 1
	v_and_b32_e32 v166, 0x5f, v2
	v_ashrrev_i32_e32 v0, 1, v2
	v_lshrrev_b32_e32 v2, 3, v2
	s_waitcnt lgkmcnt(0)
	s_add_u32 s2, s4, s6
	v_and_b32_e32 v0, 0xffffffc0, v0
	v_and_b32_e32 v2, 4, v2
	s_addc_u32 s16, s5, s7
	v_ashrrev_i32_e32 v1, 31, v0
	s_mov_b32 s4, 0
	v_lshlrev_b32_e32 v2, 1, v2
	s_cmp_eq_u32 s3, 0
	s_cbranch_scc1 .Lmrg_nostag_in
	s_barrier
